# v109 + loop-invariant bias load of the mod-item output loop hoisted in front of the loop (no per-iteration store drain)
# speedup vs baseline: 1.0049x; 1.0049x over previous
.LBB0_151:
	s_or_b64 exec, exec, s[4:5]
	s_movk_i32 s4, 0x440
	v_cmp_gt_i32_e32 vcc, s4, v139
	s_waitcnt lgkmcnt(0)
	s_barrier
	s_and_saveexec_b64 s[4:5], vcc
	s_cbranch_execz .LBB0_83
	s_mul_i32 s6, s0, 0x66000
	v_readlane_b32 s8, v255, 36
	s_mul_hi_i32 s7, s0, 0x66000
	s_add_u32 s6, s8, s6
	v_readlane_b32 s8, v255, 37
	s_mulk_i32 s0, 0x60
	s_addc_u32 s7, s8, s7
	s_sub_i32 s0, s77, s0
	s_lshl_b32 s0, s0, 6
	s_add_i32 s80, s80, s0
	v_and_b32_e32 v3, 63, v139
	v_or_b32_e32 v0, s80, v3
	v_ashrrev_i32_e32 v1, 31, v0
	v_lshl_add_u64 v[0:1], v[0:1], 2, s[46:47]
	global_load_dword v249, v[0:1], off
	v_or_b32_e32 v2, s0, v3
	v_lshlrev_b32_e32 v3, 2, v3
	v_add_u32_e32 v4, 0x8800, v140
	s_waitcnt vmcnt(0)
.LBB0_153:
	v_and_b32_e32 v6, 0x3fffffc0, v139
	v_lshl_or_b32 v9, v6, 2, v3
	ds_read_b32 v8, v4
	ds_read2st64_b32 v[6:7], v9 offset0:153 offset1:170
	v_lshrrev_b32_e32 v5, 6, v139
	s_movk_i32 s0, 0x1800
	v_add_u32_e32 v4, 0x400, v4
	s_waitcnt lgkmcnt(0)
	v_add_f32_e32 v6, v8, v6
	v_add_f32_e32 v6, v6, v7
	ds_read_b32 v7, v9 offset:47872
	s_waitcnt lgkmcnt(0)
	v_add_f32_e32 v6, v6, v7
	v_mov_b32_e32 v7, v249
	v_add_f32_e32 v8, v6, v7
	v_mad_u64_u32 v[6:7], s[70:71], v5, s0, v[2:3]
	s_movk_i32 s0, 0x33f
	v_ashrrev_i32_e32 v7, 31, v6
	v_add_u32_e32 v5, 0x100, v139
	v_cmp_lt_i32_e32 vcc, s0, v139
	v_lshl_add_u64 v[6:7], v[6:7], 2, s[6:7]
	s_or_b64 s[68:69], vcc, s[68:69]
	v_mov_b32_e32 v139, v5
	global_store_dword v[6:7], v8, off
	s_andn2_b64 exec, exec, s[68:69]
	s_cbranch_execnz .LBB0_153
	s_branch .LBB0_83
